# P5 epilogue pass-1 residual loads in a 12-deep register ring with counted vmcnt (no rstd preload)
# baseline (speedup 1.0000x reference)
; __device__ __forceinline__ unsigned cvt_pk_bf16(float lo, float hi) { unsigned r; asm volatile("v_cvt_pk_bf16_f32 %0, %1, %2" : "=v"(r) : "v"(lo), "v"(hi)); return r; }
;     __device__ __forceinline__ void fused(f32x4 (&acc)[2][2][4][2], const Unit& u, int wr, int wc, int fr, int fq, LAS unsigned char* lds, int wid, int lane) const {
;         const int row0 = u.pm * BM + wr * 64 + fr, col0 = u.pn * BM + wc * 32 + 4 * fq, b = u.pm >> 3;
;         const float* modb = mod + (size_t)b * NMOD + col0;
;         { f32x4 gv[2][2];
; #pragma unroll
;           for (int bj = 0; bj < 2; ++bj)
; #pragma unroll
;             for (int n = 0; n < 2; ++n) gv[bj][n] = *(const f32x4*)(modb + gate_off + bj * HALF + n * 16);
; #pragma unroll
;           for (int ai = 0; ai < 2; ++ai)
; #pragma unroll
;             for (int m = 0; m < 4; ++m) { const size_t off = (size_t)(row0 + ai * HALF + m * 16) * DM + col0;
; #pragma unroll
;                 for (int bj = 0; bj < 2; ++bj)
; #pragma unroll
;                     for (int n = 0; n < 2; ++n) { const f32x4 xv = *(const f32x4*)(base + off + bj * HALF + n * 16); const f32x4 o = xv + gv[bj][n] * acc[ai][bj][m][n];
;                         u32x2 w; w.x = cvt_pk_bf16(o[0], o[1]); w.y = cvt_pk_bf16(o[2], o[3]); *(u32x2*)(x1b + off + bj * HALF + n * 16) = w; acc[ai][bj][m][n] = o; }
.LBB0_582:
	s_add_u32 s0, s34, 0xd200000
	s_addc_u32 s1, s35, 0
	s_lshl_b32 s11, s7, 5
	s_lshl_b32 s12, s8, 8
	s_or_b32 s11, s12, s11
	s_lshl_b32 s10, s6, 8
	v_and_or_b32 v144, v140, 12, s11
	s_ashr_i32 s11, s6, 3
	s_add_i32 s14, s10, s54
	s_mul_hi_i32 s13, s11, 0x6000
	s_mulk_i32 s11, 0x6000
	s_add_u32 s12, s34, s11
	v_or_b32_e32 v150, s14, v153
	s_addc_u32 s13, s35, s13
	v_ashrrev_i32_e32 v145, 31, v144
	v_ashrrev_i32_e32 v151, 31, v150
	v_lshl_add_u64 v[146:147], v[144:145], 2, s[12:13]
	s_movk_i32 s11, 0x2000
	v_lshlrev_b64 v[130:131], 10, v[150:151]
	v_add_co_u32_e32 v128, vcc, s11, v146
	v_lshl_add_u64 v[148:149], v[130:131], 0, v[144:145]
	s_nop 0
	v_addc_co_u32_e32 v129, vcc, 0, v147, vcc
	v_lshl_add_u64 v[158:159], v[148:149], 2, s[36:37]
	s_barrier
	global_load_dwordx4 v[140:143], v[128:129], off
	global_load_dwordx4 v[136:139], v[128:129], off offset:64
	global_load_dwordx4 v[132:135], v[128:129], off offset:512
	s_nop 0
	global_load_dwordx4 v[128:131], v[128:129], off offset:576
	s_mov_b64 s[98:99], 0x10000
	v_lshl_add_u64 v[178:179], v[158:159], 0, s[98:99]
	s_mov_b64 s[98:99], 0x20000
	v_lshl_add_u64 v[180:181], v[158:159], 0, s[98:99]
	s_mov_b64 s[98:99], 0x30000
	v_lshl_add_u64 v[182:183], v[158:159], 0, s[98:99]
	s_mov_b64 s[98:99], 0x80000
	v_lshl_add_u64 v[184:185], v[158:159], 0, s[98:99]
	s_mov_b64 s[98:99], 0x90000
	v_lshl_add_u64 v[186:187], v[158:159], 0, s[98:99]
	s_mov_b64 s[98:99], 0xa0000
	v_lshl_add_u64 v[188:189], v[158:159], 0, s[98:99]
	s_mov_b64 s[98:99], 0xb0000
	v_lshl_add_u64 v[190:191], v[158:159], 0, s[98:99]
	global_load_dwordx4 v[192:195], v[158:159], off
	global_load_dwordx4 v[196:199], v[158:159], off offset:64
	global_load_dwordx4 v[200:203], v[158:159], off offset:512
	global_load_dwordx4 v[204:207], v[158:159], off offset:576
	global_load_dwordx4 v[208:211], v[178:179], off
	global_load_dwordx4 v[212:215], v[178:179], off offset:64
	global_load_dwordx4 v[216:219], v[178:179], off offset:512
	global_load_dwordx4 v[220:223], v[178:179], off offset:576
	global_load_dwordx4 v[224:227], v[180:181], off
	global_load_dwordx4 v[228:231], v[180:181], off offset:64
	global_load_dwordx4 v[232:235], v[180:181], off offset:512
	global_load_dwordx4 v[236:239], v[180:181], off offset:576
	v_lshl_add_u64 v[160:161], v[148:149], 1, s[0:1]
	s_mov_b64 s[12:13], 0x20000
	s_waitcnt vmcnt(11)
	v_pk_fma_f32 v[126:127], v[126:127], v[142:143], v[194:195]
	v_pk_fma_f32 v[124:125], v[124:125], v[140:141], v[192:193]
	s_nop 0
	v_cvt_pk_bf16_f32 v154, v124, v125
	v_cvt_pk_bf16_f32 v155, v126, v127
	global_store_dwordx2 v[160:161], v[154:155], off
	global_load_dwordx4 v[192:195], v[182:183], off
	s_waitcnt vmcnt(12)
	v_pk_fma_f32 v[122:123], v[122:123], v[138:139], v[198:199]
	v_pk_fma_f32 v[120:121], v[120:121], v[136:137], v[196:197]
	s_nop 0
	v_cvt_pk_bf16_f32 v154, v120, v121
	v_cvt_pk_bf16_f32 v155, v122, v123
	global_store_dwordx2 v[160:161], v[154:155], off offset:32
	global_load_dwordx4 v[196:199], v[182:183], off offset:64
	s_waitcnt vmcnt(13)
	v_pk_fma_f32 v[118:119], v[118:119], v[134:135], v[202:203]
	v_pk_fma_f32 v[116:117], v[116:117], v[132:133], v[200:201]
	s_nop 0
	v_cvt_pk_bf16_f32 v154, v116, v117
	v_cvt_pk_bf16_f32 v155, v118, v119
	global_store_dwordx2 v[160:161], v[154:155], off offset:256
	global_load_dwordx4 v[200:203], v[182:183], off offset:512
	v_or_b32_e32 v158, 16, v150
	v_ashrrev_i32_e32 v159, 31, v158
	v_lshlrev_b64 v[158:159], 10, v[158:159]
	v_lshl_add_u64 v[158:159], v[158:159], 0, v[144:145]
	v_lshl_add_u64 v[162:163], v[158:159], 2, s[36:37]
	v_lshl_add_u64 v[158:159], v[158:159], 1, s[0:1]
	s_waitcnt vmcnt(14)
	v_pk_fma_f32 v[110:111], v[110:111], v[130:131], v[206:207]
	v_pk_fma_f32 v[108:109], v[108:109], v[128:129], v[204:205]
	s_nop 0
	v_cvt_pk_bf16_f32 v154, v108, v109
	v_cvt_pk_bf16_f32 v155, v110, v111
	global_store_dwordx2 v[160:161], v[154:155], off offset:288
	global_load_dwordx4 v[204:207], v[182:183], off offset:576
	v_or_b32_e32 v160, 32, v150
	v_ashrrev_i32_e32 v161, 31, v160
	v_lshlrev_b64 v[160:161], 10, v[160:161]
	v_lshl_add_u64 v[160:161], v[160:161], 0, v[144:145]
	v_or_b32_e32 v150, 48, v150
	v_ashrrev_i32_e32 v151, 31, v150
	v_lshlrev_b64 v[150:151], 10, v[150:151]
	v_lshl_add_u64 v[150:151], v[150:151], 0, v[144:145]
	s_waitcnt vmcnt(15)
	v_pk_fma_f32 v[114:115], v[114:115], v[142:143], v[210:211]
	v_pk_fma_f32 v[112:113], v[112:113], v[140:141], v[208:209]
	s_nop 0
	v_cvt_pk_bf16_f32 v154, v112, v113
	v_cvt_pk_bf16_f32 v155, v114, v115
	global_store_dwordx2 v[158:159], v[154:155], off
	global_load_dwordx4 v[208:211], v[184:185], off
	s_waitcnt vmcnt(16)
	v_pk_fma_f32 v[106:107], v[106:107], v[138:139], v[214:215]
	v_pk_fma_f32 v[104:105], v[104:105], v[136:137], v[212:213]
	s_nop 0
	v_cvt_pk_bf16_f32 v154, v104, v105
	v_cvt_pk_bf16_f32 v155, v106, v107
	global_store_dwordx2 v[158:159], v[154:155], off offset:32
	global_load_dwordx4 v[212:215], v[184:185], off offset:64
	s_waitcnt vmcnt(17)
	v_pk_fma_f32 v[102:103], v[102:103], v[134:135], v[218:219]
	v_pk_fma_f32 v[100:101], v[100:101], v[132:133], v[216:217]
	s_nop 0
	v_cvt_pk_bf16_f32 v154, v100, v101
	v_cvt_pk_bf16_f32 v155, v102, v103
	global_store_dwordx2 v[158:159], v[154:155], off offset:256
	global_load_dwordx4 v[216:219], v[184:185], off offset:512
	v_lshl_add_u64 v[162:163], v[160:161], 2, s[36:37]
	s_waitcnt vmcnt(18)
	v_pk_fma_f32 v[94:95], v[94:95], v[130:131], v[222:223]
	v_pk_fma_f32 v[92:93], v[92:93], v[128:129], v[220:221]
	s_nop 0
	v_cvt_pk_bf16_f32 v154, v92, v93
	v_cvt_pk_bf16_f32 v155, v94, v95
	global_store_dwordx2 v[158:159], v[154:155], off offset:288
	global_load_dwordx4 v[220:223], v[184:185], off offset:576
	v_lshl_add_u64 v[158:159], v[160:161], 1, s[0:1]
	v_lshl_add_u64 v[160:161], v[150:151], 2, s[36:37]
	v_lshl_add_u64 v[150:151], v[150:151], 1, s[0:1]
	s_waitcnt vmcnt(19)
; __device__ __forceinline__ unsigned cvt_pk_bf16(float lo, float hi) { unsigned r; asm volatile("v_cvt_pk_bf16_f32 %0, %1, %2" : "=v"(r) : "v"(lo), "v"(hi)); return r; }
;     __device__ __forceinline__ void fused(f32x4 (&acc)[2][2][4][2], const Unit& u, int wr, int wc, int fr, int fq, LAS unsigned char* lds, int wid, int lane) const {
;     ...
;             for (int m = 0; m < 4; ++m) { const size_t off = (size_t)(row0 + ai * HALF + m * 16) * DM + col0;
; #pragma unroll
;                 for (int bj = 0; bj < 2; ++bj)
; #pragma unroll
;                     for (int n = 0; n < 2; ++n) { const f32x4 xv = *(const f32x4*)(base + off + bj * HALF + n * 16); const f32x4 o = xv + gv[bj][n] * acc[ai][bj][m][n];
;                         u32x2 w; w.x = cvt_pk_bf16(o[0], o[1]); w.y = cvt_pk_bf16(o[2], o[3]); *(u32x2*)(x1b + off + bj * HALF + n * 16) = w; acc[ai][bj][m][n] = o; }
	v_pk_fma_f32 v[98:99], v[98:99], v[142:143], v[226:227]
	v_pk_fma_f32 v[96:97], v[96:97], v[140:141], v[224:225]
	s_nop 0
	v_cvt_pk_bf16_f32 v154, v96, v97
	v_cvt_pk_bf16_f32 v155, v98, v99
	global_store_dwordx2 v[158:159], v[154:155], off
	global_load_dwordx4 v[224:227], v[186:187], off
	s_waitcnt vmcnt(20)
	v_pk_fma_f32 v[90:91], v[90:91], v[138:139], v[230:231]
	v_pk_fma_f32 v[88:89], v[88:89], v[136:137], v[228:229]
	s_nop 0
	v_cvt_pk_bf16_f32 v154, v88, v89
	v_cvt_pk_bf16_f32 v155, v90, v91
	global_store_dwordx2 v[158:159], v[154:155], off offset:32
	global_load_dwordx4 v[228:231], v[186:187], off offset:64
	s_waitcnt vmcnt(21)
	v_pk_fma_f32 v[86:87], v[86:87], v[134:135], v[234:235]
	v_pk_fma_f32 v[84:85], v[84:85], v[132:133], v[232:233]
	s_nop 0
	v_cvt_pk_bf16_f32 v154, v84, v85
	v_cvt_pk_bf16_f32 v155, v86, v87
	global_store_dwordx2 v[158:159], v[154:155], off offset:256
	global_load_dwordx4 v[232:235], v[186:187], off offset:512
	s_waitcnt vmcnt(22)
	v_pk_fma_f32 v[78:79], v[78:79], v[130:131], v[238:239]
	v_pk_fma_f32 v[76:77], v[76:77], v[128:129], v[236:237]
	s_nop 0
	v_cvt_pk_bf16_f32 v154, v76, v77
	v_cvt_pk_bf16_f32 v155, v78, v79
	global_store_dwordx2 v[158:159], v[154:155], off offset:288
	global_load_dwordx4 v[236:239], v[186:187], off offset:576
	v_lshl_add_u64 v[158:159], v[148:149], 0, s[12:13]
	s_mov_b64 s[12:13], 0x24000
	s_waitcnt vmcnt(22)
	v_pk_fma_f32 v[82:83], v[82:83], v[142:143], v[194:195]
	v_pk_fma_f32 v[80:81], v[80:81], v[140:141], v[192:193]
	s_nop 0
	v_cvt_pk_bf16_f32 v154, v80, v81
	v_cvt_pk_bf16_f32 v155, v82, v83
	global_store_dwordx2 v[150:151], v[154:155], off
	global_load_dwordx4 v[192:195], v[188:189], off
	s_waitcnt vmcnt(22)
	v_pk_fma_f32 v[74:75], v[74:75], v[138:139], v[198:199]
	v_pk_fma_f32 v[72:73], v[72:73], v[136:137], v[196:197]
	s_nop 0
	v_cvt_pk_bf16_f32 v154, v72, v73
	v_cvt_pk_bf16_f32 v155, v74, v75
	global_store_dwordx2 v[150:151], v[154:155], off offset:32
	global_load_dwordx4 v[196:199], v[188:189], off offset:64
	s_waitcnt vmcnt(22)
	v_pk_fma_f32 v[70:71], v[70:71], v[134:135], v[202:203]
	v_pk_fma_f32 v[68:69], v[68:69], v[132:133], v[200:201]
	s_nop 0
	v_cvt_pk_bf16_f32 v154, v68, v69
	v_cvt_pk_bf16_f32 v155, v70, v71
	global_store_dwordx2 v[150:151], v[154:155], off offset:256
	global_load_dwordx4 v[200:203], v[188:189], off offset:512
	v_lshl_add_u64 v[160:161], v[158:159], 2, s[36:37]
	s_waitcnt vmcnt(22)
	v_pk_fma_f32 v[66:67], v[66:67], v[130:131], v[206:207]
	v_pk_fma_f32 v[64:65], v[64:65], v[128:129], v[204:205]
	s_nop 0
	v_cvt_pk_bf16_f32 v154, v64, v65
	v_cvt_pk_bf16_f32 v155, v66, v67
	global_store_dwordx2 v[150:151], v[154:155], off offset:288
	global_load_dwordx4 v[204:207], v[188:189], off offset:576
	v_lshl_add_u64 v[150:151], v[158:159], 1, s[0:1]
	v_lshl_add_u64 v[158:159], v[148:149], 0, s[12:13]
	s_mov_b64 s[12:13], 0x28000
	s_waitcnt vmcnt(22)
	v_pk_fma_f32 v[62:63], v[62:63], v[142:143], v[210:211]
	v_pk_fma_f32 v[60:61], v[60:61], v[140:141], v[208:209]
	s_nop 0
	v_cvt_pk_bf16_f32 v154, v60, v61
	v_cvt_pk_bf16_f32 v155, v62, v63
	global_store_dwordx2 v[150:151], v[154:155], off
	s_waitcnt vmcnt(21)
	v_pk_fma_f32 v[58:59], v[58:59], v[138:139], v[214:215]
	v_pk_fma_f32 v[56:57], v[56:57], v[136:137], v[212:213]
	s_nop 0
	v_cvt_pk_bf16_f32 v154, v56, v57
	v_cvt_pk_bf16_f32 v155, v58, v59
	global_store_dwordx2 v[150:151], v[154:155], off offset:32
	s_waitcnt vmcnt(20)
	v_pk_fma_f32 v[54:55], v[54:55], v[134:135], v[218:219]
	v_pk_fma_f32 v[52:53], v[52:53], v[132:133], v[216:217]
	s_nop 0
	v_cvt_pk_bf16_f32 v154, v52, v53
	v_cvt_pk_bf16_f32 v155, v54, v55
	global_store_dwordx2 v[150:151], v[154:155], off offset:256
	v_lshl_add_u64 v[160:161], v[158:159], 2, s[36:37]
	s_waitcnt vmcnt(19)
	v_pk_fma_f32 v[46:47], v[46:47], v[130:131], v[222:223]
	v_pk_fma_f32 v[44:45], v[44:45], v[128:129], v[220:221]
	s_nop 0
	v_cvt_pk_bf16_f32 v154, v44, v45
	v_cvt_pk_bf16_f32 v155, v46, v47
	global_store_dwordx2 v[150:151], v[154:155], off offset:288
	v_lshl_add_u64 v[150:151], v[158:159], 1, s[0:1]
	v_lshl_add_u64 v[158:159], v[148:149], 0, s[12:13]
	s_mov_b64 s[12:13], 0x2c000
	s_waitcnt vmcnt(18)
	v_pk_fma_f32 v[50:51], v[50:51], v[142:143], v[226:227]
	v_pk_fma_f32 v[48:49], v[48:49], v[140:141], v[224:225]
	s_nop 0
	v_cvt_pk_bf16_f32 v154, v48, v49
	v_cvt_pk_bf16_f32 v155, v50, v51
	global_store_dwordx2 v[150:151], v[154:155], off
	s_waitcnt vmcnt(17)
	v_pk_fma_f32 v[42:43], v[42:43], v[138:139], v[230:231]
	v_pk_fma_f32 v[40:41], v[40:41], v[136:137], v[228:229]
	s_nop 0
	v_cvt_pk_bf16_f32 v154, v40, v41
	v_cvt_pk_bf16_f32 v155, v42, v43
	global_store_dwordx2 v[150:151], v[154:155], off offset:32
	s_waitcnt vmcnt(16)
; __device__ __forceinline__ unsigned cvt_pk_bf16(float lo, float hi) { unsigned r; asm volatile("v_cvt_pk_bf16_f32 %0, %1, %2" : "=v"(r) : "v"(lo), "v"(hi)); return r; }
;     __device__ __forceinline__ void run(const f32x4 (&v)[2][2][4][2], const Unit& u, int wr, int wc, int fr, int fq, LAS unsigned char* lds, int wid, int lane) const {
;     ...
;             for (int m = 0; m < 4; ++m) { float s = 0.f;
; #pragma unroll
;                 for (int bj = 0; bj < 2; ++bj)
; #pragma unroll
;                     for (int n = 0; n < 2; ++n) { const f32x4 x = v[ai][bj][m][n]; s += (x[0] * x[0] + x[1] * x[1]) + (x[2] * x[2] + x[3] * x[3]); }
;                 s += __shfl_xor(s, 16); s += __shfl_xor(s, 32);
;                 if (fq == 0) P[(ai * HALF + wr * 64 + m * 16 + fr) * 4 + wc] = s; }
;     __device__ __forceinline__ void fused(f32x4 (&acc)[2][2][4][2], const Unit& u, int wr, int wc, int fr, int fq, LAS unsigned char* lds, int wid, int lane) const {
;     ...
;             for (int m = 0; m < 4; ++m) { const size_t off = (size_t)(row0 + ai * HALF + m * 16) * DM + col0;
; #pragma unroll
;                 for (int bj = 0; bj < 2; ++bj)
; #pragma unroll
;                     for (int n = 0; n < 2; ++n) { const f32x4 xv = *(const f32x4*)(base + off + bj * HALF + n * 16); const f32x4 o = xv + gv[bj][n] * acc[ai][bj][m][n];
;                         u32x2 w; w.x = cvt_pk_bf16(o[0], o[1]); w.y = cvt_pk_bf16(o[2], o[3]); *(u32x2*)(x1b + off + bj * HALF + n * 16) = w; acc[ai][bj][m][n] = o; }
	v_pk_fma_f32 v[38:39], v[38:39], v[134:135], v[234:235]
	v_pk_fma_f32 v[36:37], v[36:37], v[132:133], v[232:233]
	s_nop 0
	v_cvt_pk_bf16_f32 v154, v36, v37
	v_cvt_pk_bf16_f32 v155, v38, v39
	global_store_dwordx2 v[150:151], v[154:155], off offset:256
	v_lshl_add_u64 v[160:161], v[158:159], 2, s[36:37]
	s_waitcnt vmcnt(15)
	v_pk_fma_f32 v[30:31], v[30:31], v[130:131], v[238:239]
	v_pk_fma_f32 v[28:29], v[28:29], v[128:129], v[236:237]
	s_nop 0
	v_cvt_pk_bf16_f32 v154, v28, v29
	v_cvt_pk_bf16_f32 v155, v30, v31
	global_store_dwordx2 v[150:151], v[154:155], off offset:288
	v_lshl_add_u64 v[150:151], v[158:159], 1, s[0:1]
	v_lshl_add_u64 v[158:159], v[148:149], 0, s[12:13]
	s_waitcnt vmcnt(14)
	v_pk_fma_f32 v[34:35], v[34:35], v[142:143], v[194:195]
	v_pk_fma_f32 v[32:33], v[32:33], v[140:141], v[192:193]
	s_nop 0
	v_cvt_pk_bf16_f32 v154, v32, v33
	v_cvt_pk_bf16_f32 v155, v34, v35
	global_store_dwordx2 v[150:151], v[154:155], off
	s_waitcnt vmcnt(13)
	v_pk_fma_f32 v[26:27], v[26:27], v[138:139], v[198:199]
	v_pk_fma_f32 v[24:25], v[24:25], v[136:137], v[196:197]
	s_nop 0
	v_cvt_pk_bf16_f32 v154, v24, v25
	v_cvt_pk_bf16_f32 v155, v26, v27
	global_store_dwordx2 v[150:151], v[154:155], off offset:32
	s_waitcnt vmcnt(12)
	v_pk_fma_f32 v[22:23], v[22:23], v[134:135], v[202:203]
	v_pk_fma_f32 v[20:21], v[20:21], v[132:133], v[200:201]
	s_nop 0
	v_cvt_pk_bf16_f32 v154, v20, v21
	v_cvt_pk_bf16_f32 v155, v22, v23
	global_store_dwordx2 v[150:151], v[154:155], off offset:256
	v_lshl_add_u64 v[160:161], v[158:159], 2, s[36:37]
	s_waitcnt vmcnt(11)
	v_pk_fma_f32 v[14:15], v[14:15], v[130:131], v[206:207]
	v_pk_fma_f32 v[12:13], v[12:13], v[128:129], v[204:205]
	v_lshl_add_u64 v[154:155], v[158:159], 1, s[0:1]
	v_cvt_pk_bf16_f32 v148, v12, v13
	v_cvt_pk_bf16_f32 v149, v14, v15
	global_store_dwordx2 v[150:151], v[148:149], off offset:288
	global_load_dwordx4 v[148:151], v[160:161], off
	s_lshl_b32 s0, s7, 2
	s_add_i32 s7, s0, 0
	s_waitcnt vmcnt(0)
	v_pk_fma_f32 v[142:143], v[18:19], v[142:143], v[150:151]
	v_pk_fma_f32 v[140:141], v[16:17], v[140:141], v[148:149]
	s_nop 0
	v_cvt_pk_bf16_f32 v16, v140, v141
	v_cvt_pk_bf16_f32 v17, v142, v143
	global_store_dwordx2 v[154:155], v[16:17], off
	global_load_dwordx4 v[148:151], v[160:161], off offset:64
	s_waitcnt vmcnt(0)
	v_pk_fma_f32 v[16:17], v[10:11], v[138:139], v[150:151]
	v_pk_fma_f32 v[18:19], v[8:9], v[136:137], v[148:149]
	s_nop 0
	v_cvt_pk_bf16_f32 v8, v18, v19
	v_cvt_pk_bf16_f32 v9, v16, v17
	global_store_dwordx2 v[154:155], v[8:9], off offset:32
	global_load_dwordx4 v[136:139], v[160:161], off offset:512
	s_waitcnt vmcnt(0)
	v_pk_fma_f32 v[8:9], v[6:7], v[134:135], v[138:139]
	v_pk_fma_f32 v[10:11], v[4:5], v[132:133], v[136:137]
	v_mul_f32_e32 v7, v127, v127
	v_cvt_pk_bf16_f32 v4, v10, v11
	v_cvt_pk_bf16_f32 v5, v8, v9
	global_store_dwordx2 v[154:155], v[4:5], off offset:256
	global_load_dwordx4 v[136:139], v[160:161], off offset:576
	v_mbcnt_lo_u32_b32 v4, -1, 0
	v_mbcnt_hi_u32_b32 v4, -1, v4
	v_and_b32_e32 v6, 64, v4
	v_xor_b32_e32 v5, 16, v4
	v_add_u32_e32 v6, 64, v6
	v_cmp_lt_i32_e32 vcc, v5, v6
	v_fmac_f32_e32 v7, v126, v126
	v_mul_f32_e32 v134, v123, v123
	v_cndmask_b32_e32 v5, v4, v5, vcc
	v_lshlrev_b32_e32 v133, 2, v5
	v_mul_f32_e32 v5, v125, v125
	v_fmac_f32_e32 v5, v124, v124
	v_add_f32_e32 v5, v5, v7
	v_mul_f32_e32 v7, v121, v121
	v_fmac_f32_e32 v7, v120, v120
	v_fmac_f32_e32 v134, v122, v122
	v_add_f32_e32 v7, v7, v134
	v_add_f32_e32 v5, v5, v7
	v_mul_f32_e32 v7, v117, v117
	v_mul_f32_e32 v134, v119, v119
	v_fmac_f32_e32 v7, v116, v116
	v_fmac_f32_e32 v134, v118, v118
	v_add_f32_e32 v7, v7, v134
	v_add_f32_e32 v5, v5, v7
	v_mul_f32_e32 v7, v109, v109
	v_mul_f32_e32 v134, v111, v111
	v_fmac_f32_e32 v7, v108, v108
	v_fmac_f32_e32 v134, v110, v110
	v_add_f32_e32 v7, v7, v134
	v_add_f32_e32 v5, v5, v7
	ds_bpermute_b32 v7, v133, v5
	v_xor_b32_e32 v134, 32, v4
	v_cmp_lt_i32_e32 vcc, v134, v6
	v_and_b32_e32 v132, 63, v170
	s_waitcnt lgkmcnt(0)
	v_add_f32_e32 v135, v5, v7
	v_cndmask_b32_e32 v4, v4, v134, vcc
	v_lshlrev_b32_e32 v134, 2, v4
	v_cmp_gt_u32_e32 vcc, 16, v132
	s_waitcnt vmcnt(0)
	v_pk_fma_f32 v[6:7], v[0:1], v[128:129], v[136:137]
	s_nop 0
	v_cvt_pk_bf16_f32 v0, v6, v7
	v_pk_fma_f32 v[4:5], v[2:3], v[130:131], v[138:139]
	s_nop 0
	v_cvt_pk_bf16_f32 v1, v4, v5
	global_store_dwordx2 v[154:155], v[0:1], off offset:288
	ds_bpermute_b32 v0, v134, v135
	s_and_saveexec_b64 s[0:1], vcc
	v_readlane_b32 s56, v240, 6
	v_readlane_b32 s58, v240, 8
	v_readlane_b32 s57, v240, 7
	v_readlane_b32 s59, v240, 9
	s_cbranch_execz .LBB0_584
	s_lshl_b32 s11, s51, 10
	s_add_i32 s11, s7, s11
	v_lshl_add_u32 v1, v153, 4, s11
	s_waitcnt lgkmcnt(0)
	v_add_f32_e32 v0, v135, v0
	ds_write_b32 v1, v0
